# prep o_intra (GLA and mLSTM): V^T fragments of three column tiles kept in flight with counted waits and three accumulators, instead of one LDS round trip plus dependent MFMA pair per column tile
# baseline (speedup 1.0000x reference)
.LBB0_591:
	s_or_b64 exec, exec, s[38:39]
	v_cvt_pk_bf16_f32 v0, v80, s0
	v_cndmask_b32_e64 v0, v0, 0, s[52:53]
	ds_write_b16 v149, v0 offset:38912
	v_cvt_pk_bf16_f32 v0, v81, s0
	v_cndmask_b32_e64 v0, v0, 0, s[54:55]
	ds_write_b16 v159, v0 offset:38912
	v_cvt_pk_bf16_f32 v0, v82, s0
	v_cndmask_b32_e64 v0, v0, 0, s[56:57]
	ds_write_b16 v160, v0 offset:38912
	v_cvt_pk_bf16_f32 v0, v83, s0
	v_cndmask_b32_e64 v0, v0, 0, s[58:59]
	ds_write_b16 v161, v0 offset:38912
	v_cvt_pk_bf16_f32 v0, v68, s0
	v_cndmask_b32_e64 v0, v0, 0, s[2:3]
	ds_write_b16 v149, v0 offset:38944
	v_cvt_pk_bf16_f32 v0, v69, s0
	v_cndmask_b32_e64 v0, v0, 0, s[8:9]
	ds_write_b16 v159, v0 offset:38944
	v_cvt_pk_bf16_f32 v0, v70, s0
	v_cndmask_b32_e64 v0, v0, 0, s[10:11]
	ds_write_b16 v160, v0 offset:38944
	v_cvt_pk_bf16_f32 v0, v71, s0
	v_cndmask_b32_e64 v0, v0, 0, s[12:13]
	ds_write_b16 v161, v0 offset:38944
	v_cvt_pk_bf16_f32 v0, v72, s0
	v_cndmask_b32_e64 v0, v0, 0, s[14:15]
	ds_write_b16 v149, v0 offset:38976
	v_cvt_pk_bf16_f32 v0, v73, s0
	v_cndmask_b32_e64 v0, v0, 0, s[18:19]
	ds_write_b16 v159, v0 offset:38976
	v_cvt_pk_bf16_f32 v0, v74, s0
	v_cndmask_b32_e64 v0, v0, 0, s[22:23]
	ds_write_b16 v160, v0 offset:38976
	v_cvt_pk_bf16_f32 v0, v75, s0
	v_cndmask_b32_e64 v0, v0, 0, s[24:25]
	ds_write_b16 v161, v0 offset:38976
	v_cvt_pk_bf16_f32 v0, v76, s0
	v_cndmask_b32_e64 v0, v0, 0, s[26:27]
	ds_write_b16 v149, v0 offset:39008
	v_cvt_pk_bf16_f32 v0, v77, s0
	v_cndmask_b32_e64 v0, v0, 0, s[28:29]
	ds_write_b16 v159, v0 offset:39008
	v_cvt_pk_bf16_f32 v0, v78, s0
	v_cndmask_b32_e64 v0, v0, 0, s[30:31]
	ds_write_b16 v160, v0 offset:39008
	v_cvt_pk_bf16_f32 v0, v79, s0
	v_cndmask_b32_e64 v0, v0, 0, s[34:35]
	ds_write_b16 v161, v0 offset:39008
	s_waitcnt lgkmcnt(0)
	s_barrier
	ds_read_b128 v[72:75], v147 offset:38912
	ds_read_b128 v[68:71], v147 offset:38976
	ds_read_b64_tr_b16 v[76:77], v163 offset:48128
	ds_read_b64_tr_b16 v[78:79], v163 offset:48960
	ds_read_b64_tr_b16 v[80:81], v163 offset:54784
	ds_read_b64_tr_b16 v[82:83], v163 offset:55616
	ds_read_b64_tr_b16 v[84:85], v163 offset:48160
	ds_read_b64_tr_b16 v[86:87], v163 offset:48992
	ds_read_b64_tr_b16 v[88:89], v163 offset:54816
	ds_read_b64_tr_b16 v[90:91], v163 offset:55648
	ds_read_b64_tr_b16 v[234:235], v163 offset:48192
	ds_read_b64_tr_b16 v[236:237], v163 offset:49024
	ds_read_b64_tr_b16 v[238:239], v163 offset:54848
	ds_read_b64_tr_b16 v[240:241], v163 offset:55680
	s_mul_i32 s38, s73, 0x3180000
	s_add_u32 s38, s70, s38
	s_addc_u32 s39, s71, 0
	v_cndmask_b32_e64 v0, v162, v146, s[64:65]
	v_or_b32_e32 v0, v0, v190
	v_mov_b64_e32 v[2:3], s[38:39]
	s_nop 0
	v_mad_i64_i32 v[2:3], s[38:39], v0, s16, v[2:3]
	v_mov_b32_e32 v121, v1
	v_lshl_add_u64 v[2:3], v[2:3], 0, v[120:121]
	v_mov_b32_e32 v107, v1
	v_lshl_add_u64 v[2:3], v[2:3], 0, v[106:107]
	s_mov_b32 s73, 1
	s_mov_b64 s[64:65], 0
	s_waitcnt lgkmcnt(10)
	v_mfma_f32_16x16x32_bf16 v[242:245], v[76:79], v[72:75], 0
	s_waitcnt lgkmcnt(8)
	v_mfma_f32_16x16x32_bf16 v[242:245], v[80:83], v[68:71], v[242:245]
	s_waitcnt lgkmcnt(6)
	v_mfma_f32_16x16x32_bf16 v[246:249], v[84:87], v[72:75], 0
	s_waitcnt lgkmcnt(4)
	v_mfma_f32_16x16x32_bf16 v[246:249], v[88:91], v[68:71], v[246:249]
	ds_read_b64_tr_b16 v[76:77], v163 offset:48224
	ds_read_b64_tr_b16 v[78:79], v163 offset:49056
	ds_read_b64_tr_b16 v[80:81], v163 offset:54880
	ds_read_b64_tr_b16 v[82:83], v163 offset:55712
	s_waitcnt lgkmcnt(6)
	v_mfma_f32_16x16x32_bf16 v[250:253], v[234:237], v[72:75], 0
	s_waitcnt lgkmcnt(4)
	v_mfma_f32_16x16x32_bf16 v[250:253], v[238:241], v[68:71], v[250:253]
	ds_read_b64_tr_b16 v[84:85], v163 offset:48256
	ds_read_b64_tr_b16 v[86:87], v163 offset:49088
	ds_read_b64_tr_b16 v[88:89], v163 offset:54912
	ds_read_b64_tr_b16 v[90:91], v163 offset:55744
	s_nop 3
	v_cvt_pk_bf16_f32 v202, v242, v243
	v_cvt_pk_bf16_f32 v203, v244, v245
	global_store_dwordx2 v[2:3], v[202:203], off
	ds_read_b64_tr_b16 v[234:235], v163 offset:48288
	ds_read_b64_tr_b16 v[236:237], v163 offset:49120
	ds_read_b64_tr_b16 v[238:239], v163 offset:54944
	ds_read_b64_tr_b16 v[240:241], v163 offset:55776
	v_cvt_pk_bf16_f32 v204, v246, v247
	v_cvt_pk_bf16_f32 v205, v248, v249
	global_store_dwordx2 v[2:3], v[204:205], off offset:32
	s_and_b64 vcc, exec, s[62:63]
	s_waitcnt lgkmcnt(10)
	v_mfma_f32_16x16x32_bf16 v[242:245], v[76:79], v[72:75], 0
	s_waitcnt lgkmcnt(8)
	v_mfma_f32_16x16x32_bf16 v[242:245], v[80:83], v[68:71], v[242:245]
	v_cvt_pk_bf16_f32 v202, v250, v251
	v_cvt_pk_bf16_f32 v203, v252, v253
	global_store_dwordx2 v[2:3], v[202:203], off offset:64
	s_waitcnt lgkmcnt(6)
	v_mfma_f32_16x16x32_bf16 v[246:249], v[84:87], v[72:75], 0
	s_waitcnt lgkmcnt(4)
	v_mfma_f32_16x16x32_bf16 v[246:249], v[88:91], v[68:71], v[246:249]
	s_waitcnt lgkmcnt(2)
	v_mfma_f32_16x16x32_bf16 v[250:253], v[234:237], v[72:75], 0
	s_waitcnt lgkmcnt(0)
	v_mfma_f32_16x16x32_bf16 v[250:253], v[238:241], v[68:71], v[250:253]
	v_cvt_pk_bf16_f32 v204, v242, v243
	v_cvt_pk_bf16_f32 v205, v244, v245
	global_store_dwordx2 v[2:3], v[204:205], off offset:96
	s_nop 7
	v_cvt_pk_bf16_f32 v202, v246, v247
	v_cvt_pk_bf16_f32 v203, v248, v249
	global_store_dwordx2 v[2:3], v[202:203], off offset:128
	s_nop 7
	s_nop 3
	v_cvt_pk_bf16_f32 v204, v250, v251
	v_cvt_pk_bf16_f32 v205, v252, v253
	global_store_dwordx2 v[2:3], v[204:205], off offset:160
	s_cbranch_vccnz .LBB0_583

.LBB0_629:
	s_or_b64 exec, exec, s[38:39]
	s_waitcnt lgkmcnt(0)
	s_barrier
	ds_read_b128 v[80:83], v164 offset:39936
	ds_read_b128 v[76:79], v164 offset:40000
	ds_read_b64_tr_b16 v[84:85], v165 offset:26624
	ds_read_b64_tr_b16 v[86:87], v165 offset:27456
	ds_read_b64_tr_b16 v[88:89], v165 offset:33280
	ds_read_b64_tr_b16 v[90:91], v165 offset:34112
	ds_read_b64_tr_b16 v[176:177], v165 offset:26656
	ds_read_b64_tr_b16 v[178:179], v165 offset:27488
	ds_read_b64_tr_b16 v[180:181], v165 offset:33312
	ds_read_b64_tr_b16 v[182:183], v165 offset:34144
	ds_read_b64_tr_b16 v[184:185], v165 offset:26688
	ds_read_b64_tr_b16 v[186:187], v165 offset:27520
	ds_read_b64_tr_b16 v[188:189], v165 offset:33344
	ds_read_b64_tr_b16 v[190:191], v165 offset:34176
	s_mul_i32 s1, s76, 0x3180000
	s_add_u32 s38, s86, s1
	s_addc_u32 s39, s87, 0
	v_cndmask_b32_e64 v0, v125, v135, s[70:71]
	v_or_b32_e32 v0, v0, v171
	v_mov_b64_e32 v[2:3], s[38:39]
	s_nop 0
	v_mad_i64_i32 v[2:3], s[38:39], v0, s16, v[2:3]
	v_mov_b32_e32 v121, v1
	v_lshl_add_u64 v[2:3], v[2:3], 0, v[120:121]
	v_mov_b32_e32 v115, v1
	v_lshl_add_u64 v[92:93], v[2:3], 0, v[114:115]
	s_mov_b32 s1, 0xc600000
	s_mov_b64 s[38:39], 0xc600300
	v_add_co_u32_e32 v248, vcc, s1, v92
	s_nop 1
	v_addc_co_u32_e32 v249, vcc, 0, v93, vcc
	v_lshl_add_u64 v[2:3], v[92:93], 0, s[38:39]
	s_mov_b32 s76, 1
	s_mov_b64 s[70:71], 0
	s_waitcnt lgkmcnt(10)
	v_mfma_f32_16x16x32_bf16 v[192:195], v[84:87], v[80:83], 0
	s_waitcnt lgkmcnt(8)
	v_mfma_f32_16x16x32_bf16 v[192:195], v[88:91], v[76:79], v[192:195]
	s_waitcnt lgkmcnt(6)
	v_mfma_f32_16x16x32_bf16 v[196:199], v[176:179], v[80:83], 0
	s_waitcnt lgkmcnt(4)
	v_mfma_f32_16x16x32_bf16 v[196:199], v[180:183], v[76:79], v[196:199]
	ds_read_b64_tr_b16 v[84:85], v165 offset:26720
	ds_read_b64_tr_b16 v[86:87], v165 offset:27552
	ds_read_b64_tr_b16 v[88:89], v165 offset:33376
	ds_read_b64_tr_b16 v[90:91], v165 offset:34208
	s_waitcnt lgkmcnt(6)
	v_mfma_f32_16x16x32_bf16 v[200:203], v[184:187], v[80:83], 0
	s_waitcnt lgkmcnt(4)
	v_mfma_f32_16x16x32_bf16 v[200:203], v[188:191], v[76:79], v[200:203]
	ds_read_b64_tr_b16 v[176:177], v165 offset:26752
	ds_read_b64_tr_b16 v[178:179], v165 offset:27584
	ds_read_b64_tr_b16 v[180:181], v165 offset:33408
	ds_read_b64_tr_b16 v[182:183], v165 offset:34240
	s_nop 3
	v_cvt_pk_bf16_f32 v244, v192, v193
	v_cvt_pk_bf16_f32 v245, v194, v195
	global_store_dwordx2 v[248:249], v[244:245], off offset:768
	ds_read_b64_tr_b16 v[184:185], v165 offset:26784
	ds_read_b64_tr_b16 v[186:187], v165 offset:27616
	ds_read_b64_tr_b16 v[188:189], v165 offset:33440
	ds_read_b64_tr_b16 v[190:191], v165 offset:34272
	v_cvt_pk_bf16_f32 v246, v196, v197
	v_cvt_pk_bf16_f32 v247, v198, v199
	global_store_dwordx2 v[2:3], v[246:247], off offset:32
	s_and_b64 vcc, exec, s[96:97]
	s_waitcnt lgkmcnt(10)
	v_mfma_f32_16x16x32_bf16 v[192:195], v[84:87], v[80:83], 0
	s_waitcnt lgkmcnt(8)
	v_mfma_f32_16x16x32_bf16 v[192:195], v[88:91], v[76:79], v[192:195]
	v_cvt_pk_bf16_f32 v244, v200, v201
	v_cvt_pk_bf16_f32 v245, v202, v203
	global_store_dwordx2 v[2:3], v[244:245], off offset:64
	s_waitcnt lgkmcnt(6)
	v_mfma_f32_16x16x32_bf16 v[196:199], v[176:179], v[80:83], 0
	s_waitcnt lgkmcnt(4)
	v_mfma_f32_16x16x32_bf16 v[196:199], v[180:183], v[76:79], v[196:199]
	s_waitcnt lgkmcnt(2)
	v_mfma_f32_16x16x32_bf16 v[200:203], v[184:187], v[80:83], 0
	s_waitcnt lgkmcnt(0)
	v_mfma_f32_16x16x32_bf16 v[200:203], v[188:191], v[76:79], v[200:203]
	v_cvt_pk_bf16_f32 v246, v192, v193
	v_cvt_pk_bf16_f32 v247, v194, v195
	global_store_dwordx2 v[2:3], v[246:247], off offset:96
	s_nop 7
	v_cvt_pk_bf16_f32 v244, v196, v197
	v_cvt_pk_bf16_f32 v245, v198, v199
	global_store_dwordx2 v[2:3], v[244:245], off offset:128
	s_nop 7
	s_nop 3
	v_cvt_pk_bf16_f32 v246, v200, v201
	v_cvt_pk_bf16_f32 v247, v202, v203
	global_store_dwordx2 v[2:3], v[246:247], off offset:160
	s_cbranch_vccnz .LBB0_619
